# projection phases: alternate workgroups start about 4.5 us late (half the previous offset)
# baseline (speedup 1.0000x reference)
; __global__ void __launch_bounds__(512, 2) mk_fwd(Args args) {
;     ...
;             const int l = __builtin_amdgcn_readfirstlane((ph - 1) >> 3), s = __builtin_amdgcn_readfirstlane((ph - 1) & 7);
;     ...
;             if (s == 3) mixers_phase(C, l, shm, rep ? REP_SUB : 7);
;     ...
;             if (s == 3) {}
;     ...
;             else {
;                 unsigned char* wl = args.ws + WS_W + (size_t)l * W_LAYER;
;                 pg8::Gemm g; pg8::Sched S; pg8::EpiDesc E;
;                 S.nM = MP / 256; S.G = gridDim.x; S.c = blockIdx.x; S.segs = 1;
;                 E.l = l; E.final_ = 0; E.alpha = 1.f; E.rss_in = C.RSS; E.rss_out = C.RSS;
;                 if (s == 0 || s == 6) { g.A = C.XB; g.lda = DM; g.Bt = (const bf16_t*)(wl + (s == 0 ? W_GU1 : W_GU2)); g.ldb = DM; S.nN = NIN / 256; S.nt_full = DM / 64; E.kind = pg8::EK_SWIGLU; E.rss_in = C.RSS + (size_t)(3 * l + (s == 0 ? 0 : 2)) * MP; }
;                 else if (s == 1 || s == 7) { g.A = C.ACT; g.lda = DFF; g.Bt = (const bf16_t*)(wl + (s == 1 ? W_DN1 : W_DN2)); g.ldb = DFF; S.nN = 4; S.nt_full = DFF / 64; E.kind = pg8::EK_RESID; E.alpha = 0.5f; E.rss_out = C.RSS + (size_t)(3 * l + (s == 1 ? 1 : 3)) * MP; E.final_ = (s == 7 && l == 1); }
;                 else if (s == 2) { g.A = C.XB; g.lda = DM; g.Bt = (const bf16_t*)(wl + W_IN); g.ldb = DM; S.nN = NIN / 256; S.nt_full = DM / 64; E.kind = pg8::EK_PROJ; E.rss_in = C.RSS + (size_t)(3 * l + 1) * MP; }
.LBB0_16:
	v_readlane_b32 s0, v254, 47
	v_readlane_b32 s1, v254, 48
	s_and_b64 vcc, exec, s[0:1]
	s_cbranch_vccz .LBB0_29
	v_readlane_b32 s0, v252, 63
	s_add_i32 s35, s0, -1
	v_readlane_b32 s1, v253, 0
	s_ashr_i32 s0, s35, 3
	v_writelane_b32 v254, s0, 51
	s_and_b32 s34, s35, 7
	s_cmp_lg_u32 s34, 3
	v_writelane_b32 v254, s1, 52
	v_writelane_b32 v254, s72, 53
	s_mov_b64 s[0:1], -1
	s_nop 0
	v_writelane_b32 v254, s73, 54
	v_writelane_b32 v254, s74, 55
	v_writelane_b32 v254, s75, 56
	v_writelane_b32 v254, s76, 57
	v_writelane_b32 v254, s77, 58
	v_writelane_b32 v254, s78, 59
	v_writelane_b32 v254, s79, 60
	v_writelane_b32 v251, s83, 0
	v_writelane_b32 v254, s80, 61
	v_writelane_b32 v251, s84, 1
	v_writelane_b32 v254, s81, 62
	v_writelane_b32 v251, s85, 2
	v_writelane_b32 v254, s82, 63
	v_writelane_b32 v251, s86, 3
	v_writelane_b32 v251, s87, 4
	s_cbranch_scc0 .LBB0_503
	s_cmp_eq_u32 s34, 2
	s_cbranch_scc0 .Lskew_done
	v_readlane_b32 s0, v252, 0
	s_lshr_b32 s0, s0, 3
	s_lshr_b32 s1, s0, 3
	s_add_i32 s0, s0, s1
	s_and_b32 s0, s0, 1
	s_cmp_eq_u32 s0, 0
	s_cbranch_scc1 .Lskew_done
	s_sleep 127
.Lskew_done:
	v_readlane_b32 s0, v254, 51
	v_readlane_b32 s1, v254, 52
	s_mov_b32 s2, s0
	s_mul_i32 s1, s2, 0x3000000
	s_mul_hi_i32 s0, s0, 0x3000000
	s_add_u32 s18, s96, s1
	s_addc_u32 s26, s97, s0
	s_cmp_lt_i32 s34, 4
	s_mov_b64 s[6:7], -1
	s_mov_b64 s[20:21], 0
	s_mov_b64 s[2:3], 0
	s_mov_b64 s[10:11], 0
	s_mov_b64 s[8:9], 0
	s_cbranch_scc1 .LBB0_25
	s_mov_b64 s[0:1], -1
	s_cmp_gt_i32 s34, 5
	s_cbranch_scc0 .LBB0_21
	s_cmp_gt_i32 s34, 6
	s_mov_b64 s[0:1], 0
	s_mov_b64 s[2:3], -1
	s_cselect_b64 s[10:11], -1, 0
